# final RMSNorm phase rewritten: gain loaded once, 16 row loads in flight
# speedup vs baseline: 1.1852x; 1.0012x over previous
; __device__ __forceinline__ int launder(int v) { asm volatile("" : "+v"(v)); return v; }
; __device__ void final_item(const Params& p, int item, const int tid_in) {
;     const int tid = launder(tid_in);
;     const int wid = tid >> 6, lane = tid & 63, r0 = item * 16 + wid, r1 = r0 + 8;
;     float* d0 = final_dst(p, r0); float* d1 = final_dst(p, r1);
;     const float* x0 = (const float*)(pws(p) + OFF_XF) + (size_t)r0 * D; const float* x1 = x0 + (size_t)8 * D;
;     f32x4 v0[8], v1[8]; float s0 = 0.f, s1 = 0.f;
; #pragma unroll
;     for (int i = 0; i < 8; ++i) { v0[i] = *(const f32x4*)(x0 + i * 256 + lane * 4); v1[i] = *(const f32x4*)(x1 + i * 256 + lane * 4); }
; #pragma unroll
;     for (int i = 0; i < 8; ++i) { s0 += v0[i][0] * v0[i][0] + v0[i][1] * v0[i][1] + v0[i][2] * v0[i][2] + v0[i][3] * v0[i][3];
;         s1 += v1[i][0] * v1[i][0] + v1[i][1] * v1[i][1] + v1[i][2] * v1[i][2] + v1[i][3] * v1[i][3]; }
;     const float rs0 = rsqrtf(wave_sum(s0) * (1.0f / 2048.0f) + EPS), rs1 = rsqrtf(wave_sum(s1) * (1.0f / 2048.0f) + EPS);
.LBB0_9:
	v_mov_b32_e32 v244, v191
	v_readlane_b32 s82, v253, 0
	s_mov_b64 s[8:9], -1
	s_mov_b64 s[0:1], 0
	s_cmp_lt_i32 s81, 13
	s_mov_b64 s[6:7], 0
	s_cbranch_scc1 .LBB0_58
	s_cmp_eq_u32 s81, 13
	s_mov_b64 s[6:7], -1
	s_cbranch_scc0 .LBB0_62
	s_cmpk_gt_i32 s82, 0x243
	s_cbranch_scc1 .LBB0_61
	v_and_b32_e32 v2, 63, v244
	v_lshlrev_b32_e32 v2, 4, v2
	v_readfirstlane_b32 s14, v244
	s_add_u32 s16, s84, 0x1000
	s_addc_u32 s17, s85, 0
	s_lshr_b32 s14, s14, 6
	global_load_dwordx4 v[100:103], v2, s[84:85]
	global_load_dwordx4 v[104:107], v2, s[84:85] offset:1024
	global_load_dwordx4 v[108:111], v2, s[84:85] offset:2048
	global_load_dwordx4 v[112:115], v2, s[84:85] offset:3072
	global_load_dwordx4 v[116:119], v2, s[16:17]
	global_load_dwordx4 v[120:123], v2, s[16:17] offset:1024
	global_load_dwordx4 v[124:127], v2, s[16:17] offset:2048
	global_load_dwordx4 v[128:131], v2, s[16:17] offset:3072
	s_lshl_b32 s12, s82, 4
	s_mov_b32 s13, s82
.Lfin_item:
	s_add_i32 s15, s12, s14
	s_lshl_b32 s0, s15, 13
	s_add_u32 s6, s76, s0
	s_addc_u32 s7, s77, 0
	s_add_u32 s8, s6, 0x1000
	s_addc_u32 s9, s7, 0
	s_add_u32 s10, s6, 0x10000
	s_addc_u32 s11, s7, 0
	s_add_u32 s18, s6, 0x11000
	s_addc_u32 s19, s7, 0
	global_load_dwordx4 v[8:11], v2, s[6:7]
	global_load_dwordx4 v[12:15], v2, s[6:7] offset:1024
	global_load_dwordx4 v[16:19], v2, s[6:7] offset:2048
	global_load_dwordx4 v[20:23], v2, s[6:7] offset:3072
	global_load_dwordx4 v[24:27], v2, s[8:9]
	global_load_dwordx4 v[28:31], v2, s[8:9] offset:1024
	global_load_dwordx4 v[32:35], v2, s[8:9] offset:2048
	global_load_dwordx4 v[36:39], v2, s[8:9] offset:3072
	global_load_dwordx4 v[40:43], v2, s[10:11]
	global_load_dwordx4 v[44:47], v2, s[10:11] offset:1024
	global_load_dwordx4 v[48:51], v2, s[10:11] offset:2048
	global_load_dwordx4 v[52:55], v2, s[10:11] offset:3072
	global_load_dwordx4 v[56:59], v2, s[18:19]
	global_load_dwordx4 v[60:63], v2, s[18:19] offset:1024
	global_load_dwordx4 v[64:67], v2, s[18:19] offset:2048
	global_load_dwordx4 v[68:71], v2, s[18:19] offset:3072
	s_mov_b32 s30, s15
	s_cmpk_lt_u32 s30, 0x400
	s_cbranch_scc1 .Lfin_d0_samp
	s_add_i32 s0, s30, 0xfffffc00
	s_mul_hi_u32 s1, s0, 0xfe03f81
	s_lshr_b32 s1, s1, 7
	s_mul_i32 s31, s1, 0x810
	s_sub_i32 s0, s0, s31
	s_cmp_gt_u32 s0, 15
	s_cselect_b32 s28, 1, 0
	s_lshl_b32 s1, s1, 11
	s_add_i32 s0, s0, s1
	s_add_i32 s0, s0, -16
	s_lshl_b32 s0, s0, 13
	s_add_u32 s20, s86, s0
	s_addc_u32 s21, s87, 0
	s_branch .Lfin_d0_done
.Lfin_d0_samp:
	s_lshl_b32 s0, s30, 13
	s_add_u32 s20, s66, s0
	s_addc_u32 s21, s67, 0
	s_mov_b32 s28, 1
.Lfin_d0_done:
	s_add_u32 s22, s20, 0x1000
	s_addc_u32 s23, s21, 0
	s_add_i32 s30, s15, 8
	s_cmpk_lt_u32 s30, 0x400
	s_cbranch_scc1 .Lfin_d1_samp
	s_add_i32 s0, s30, 0xfffffc00
	s_mul_hi_u32 s1, s0, 0xfe03f81
	s_lshr_b32 s1, s1, 7
	s_mul_i32 s31, s1, 0x810
	s_sub_i32 s0, s0, s31
	s_cmp_gt_u32 s0, 15
	s_cselect_b32 s29, 1, 0
	s_lshl_b32 s1, s1, 11
	s_add_i32 s0, s0, s1
	s_add_i32 s0, s0, -16
	s_lshl_b32 s0, s0, 13
	s_add_u32 s24, s86, s0
	s_addc_u32 s25, s87, 0
	s_branch .Lfin_d1_done
.Lfin_d1_samp:
	s_lshl_b32 s0, s30, 13
	s_add_u32 s24, s66, s0
	s_addc_u32 s25, s67, 0
	s_mov_b32 s29, 1
.Lfin_d1_done:
	s_add_u32 s26, s24, 0x1000
	s_addc_u32 s27, s25, 0
	s_waitcnt vmcnt(8)
	v_mul_f32_e32 v72, v8, v8
	v_fmac_f32_e32 v72, v9, v9
	v_fmac_f32_e32 v72, v10, v10
	v_fmac_f32_e32 v72, v11, v11
	v_fmac_f32_e32 v72, v12, v12
	v_fmac_f32_e32 v72, v13, v13
	v_fmac_f32_e32 v72, v14, v14
	v_fmac_f32_e32 v72, v15, v15
	v_fmac_f32_e32 v72, v16, v16
	v_fmac_f32_e32 v72, v17, v17
	v_fmac_f32_e32 v72, v18, v18
	v_fmac_f32_e32 v72, v19, v19
	v_fmac_f32_e32 v72, v20, v20
	v_fmac_f32_e32 v72, v21, v21
	v_fmac_f32_e32 v72, v22, v22
	v_fmac_f32_e32 v72, v23, v23
	v_fmac_f32_e32 v72, v24, v24
	v_fmac_f32_e32 v72, v25, v25
	v_fmac_f32_e32 v72, v26, v26
	v_fmac_f32_e32 v72, v27, v27
	v_fmac_f32_e32 v72, v28, v28
	v_fmac_f32_e32 v72, v29, v29
	v_fmac_f32_e32 v72, v30, v30
	v_fmac_f32_e32 v72, v31, v31
	v_fmac_f32_e32 v72, v32, v32
	v_fmac_f32_e32 v72, v33, v33
	v_fmac_f32_e32 v72, v34, v34
	v_fmac_f32_e32 v72, v35, v35
	v_fmac_f32_e32 v72, v36, v36
	v_fmac_f32_e32 v72, v37, v37
	v_fmac_f32_e32 v72, v38, v38
	v_fmac_f32_e32 v72, v39, v39
	s_waitcnt vmcnt(0)
	v_mul_f32_e32 v73, v40, v40
	v_fmac_f32_e32 v73, v41, v41
	v_fmac_f32_e32 v73, v42, v42
	v_fmac_f32_e32 v73, v43, v43
	v_fmac_f32_e32 v73, v44, v44
	v_fmac_f32_e32 v73, v45, v45
	v_fmac_f32_e32 v73, v46, v46
	v_fmac_f32_e32 v73, v47, v47
	v_fmac_f32_e32 v73, v48, v48
	v_fmac_f32_e32 v73, v49, v49
	v_fmac_f32_e32 v73, v50, v50
	v_fmac_f32_e32 v73, v51, v51
	v_fmac_f32_e32 v73, v52, v52
	v_fmac_f32_e32 v73, v53, v53
	v_fmac_f32_e32 v73, v54, v54
	v_fmac_f32_e32 v73, v55, v55
	v_fmac_f32_e32 v73, v56, v56
	v_fmac_f32_e32 v73, v57, v57
	v_fmac_f32_e32 v73, v58, v58
	v_fmac_f32_e32 v73, v59, v59
	v_fmac_f32_e32 v73, v60, v60
	v_fmac_f32_e32 v73, v61, v61
	v_fmac_f32_e32 v73, v62, v62
	v_fmac_f32_e32 v73, v63, v63
	v_fmac_f32_e32 v73, v64, v64
	v_fmac_f32_e32 v73, v65, v65
	v_fmac_f32_e32 v73, v66, v66
	v_fmac_f32_e32 v73, v67, v67
	v_fmac_f32_e32 v73, v68, v68
	v_fmac_f32_e32 v73, v69, v69
	v_fmac_f32_e32 v73, v70, v70
	v_fmac_f32_e32 v73, v71, v71
	s_nop 1
	v_add_f32_dpp v72, v72, v72 quad_perm:[1,0,3,2] row_mask:0xf bank_mask:0xf bound_ctrl:1
	v_add_f32_dpp v73, v73, v73 quad_perm:[1,0,3,2] row_mask:0xf bank_mask:0xf bound_ctrl:1
	s_nop 0
	v_add_f32_dpp v72, v72, v72 quad_perm:[2,3,0,1] row_mask:0xf bank_mask:0xf bound_ctrl:1
	v_add_f32_dpp v73, v73, v73 quad_perm:[2,3,0,1] row_mask:0xf bank_mask:0xf bound_ctrl:1
	s_nop 0
	v_add_f32_dpp v72, v72, v72 row_half_mirror row_mask:0xf bank_mask:0xf bound_ctrl:1
	v_add_f32_dpp v73, v73, v73 row_half_mirror row_mask:0xf bank_mask:0xf bound_ctrl:1
	s_nop 0
	v_add_f32_dpp v72, v72, v72 row_mirror row_mask:0xf bank_mask:0xf bound_ctrl:1
	v_add_f32_dpp v73, v73, v73 row_mirror row_mask:0xf bank_mask:0xf bound_ctrl:1
	s_nop 0
	v_readlane_b32 s0, v72, 0
	v_readlane_b32 s1, v72, 16
	v_readlane_b32 s30, v72, 32
	v_readlane_b32 s31, v72, 48
	s_nop 1
	v_mov_b32_e32 v74, s1
	v_mov_b32_e32 v75, s31
	v_add_f32_e32 v74, s0, v74
	v_add_f32_e32 v75, s30, v75
	v_add_f32_e32 v74, v74, v75
	v_readlane_b32 s0, v73, 0
	v_readlane_b32 s1, v73, 16
	v_readlane_b32 s30, v73, 32
	v_readlane_b32 s31, v73, 48
	s_nop 1
	v_mov_b32_e32 v84, s1
	v_mov_b32_e32 v75, s31
	v_add_f32_e32 v84, s0, v84
	v_add_f32_e32 v75, s30, v75
	v_add_f32_e32 v84, v84, v75
	v_mov_b32_e32 v75, 0x3a000000
	v_fma_f32 v74, v74, v75, v190
	v_fma_f32 v84, v84, v75, v190
	v_rsq_f32_e32 v74, v74
	v_rsq_f32_e32 v84, v84
	s_nop 0
	s_cmp_eq_u32 s28, 0
	s_cbranch_scc1 .Lfin_s0_skip
; __device__ void final_item(const Params& p, int item, const int tid_in) {
;     ...
; #pragma unroll
;     for (int i = 0; i < 8; ++i) { const f32x4 gg = *(const f32x4*)(p.final_norm + i * 256 + lane * 4);
;         if (d0) *(f32x4*)(d0 + i * 256 + lane * 4) = v0[i] * rs0 * gg;
;         if (d1) *(f32x4*)(d1 + i * 256 + lane * 4) = v1[i] * rs1 * gg; }
; __device__ __forceinline__ void run_phase(const Params& p, int ph, LAS unsigned char* lds, const int tid, const int bid) {
;     ...
;     if (ph == 13) { if (PH_MASK & 128) for (int it = bid; it < MR / 16; it += G) final_item(p, it, tid); return; }
	v_mul_f32_e32 v76, v74, v8
	v_mul_f32_e32 v77, v74, v9
	v_mul_f32_e32 v78, v74, v10
	v_mul_f32_e32 v79, v74, v11
	v_mul_f32_e32 v76, v76, v100
	v_mul_f32_e32 v77, v77, v101
	v_mul_f32_e32 v78, v78, v102
	v_mul_f32_e32 v79, v79, v103
	global_store_dwordx4 v2, v[76:79], s[20:21]
	v_mul_f32_e32 v80, v74, v12
	v_mul_f32_e32 v81, v74, v13
	v_mul_f32_e32 v82, v74, v14
	v_mul_f32_e32 v83, v74, v15
	v_mul_f32_e32 v80, v80, v104
	v_mul_f32_e32 v81, v81, v105
	v_mul_f32_e32 v82, v82, v106
	v_mul_f32_e32 v83, v83, v107
	global_store_dwordx4 v2, v[80:83], s[20:21] offset:1024
	v_mul_f32_e32 v76, v74, v16
	v_mul_f32_e32 v77, v74, v17
	v_mul_f32_e32 v78, v74, v18
	v_mul_f32_e32 v79, v74, v19
	v_mul_f32_e32 v76, v76, v108
	v_mul_f32_e32 v77, v77, v109
	v_mul_f32_e32 v78, v78, v110
	v_mul_f32_e32 v79, v79, v111
	global_store_dwordx4 v2, v[76:79], s[20:21] offset:2048
	v_mul_f32_e32 v80, v74, v20
	v_mul_f32_e32 v81, v74, v21
	v_mul_f32_e32 v82, v74, v22
	v_mul_f32_e32 v83, v74, v23
	v_mul_f32_e32 v80, v80, v112
	v_mul_f32_e32 v81, v81, v113
	v_mul_f32_e32 v82, v82, v114
	v_mul_f32_e32 v83, v83, v115
	global_store_dwordx4 v2, v[80:83], s[20:21] offset:3072
	v_mul_f32_e32 v76, v74, v24
	v_mul_f32_e32 v77, v74, v25
	v_mul_f32_e32 v78, v74, v26
	v_mul_f32_e32 v79, v74, v27
	v_mul_f32_e32 v76, v76, v116
	v_mul_f32_e32 v77, v77, v117
	v_mul_f32_e32 v78, v78, v118
	v_mul_f32_e32 v79, v79, v119
	global_store_dwordx4 v2, v[76:79], s[22:23]
	v_mul_f32_e32 v80, v74, v28
	v_mul_f32_e32 v81, v74, v29
	v_mul_f32_e32 v82, v74, v30
	v_mul_f32_e32 v83, v74, v31
	v_mul_f32_e32 v80, v80, v120
	v_mul_f32_e32 v81, v81, v121
	v_mul_f32_e32 v82, v82, v122
	v_mul_f32_e32 v83, v83, v123
	global_store_dwordx4 v2, v[80:83], s[22:23] offset:1024
	v_mul_f32_e32 v76, v74, v32
	v_mul_f32_e32 v77, v74, v33
	v_mul_f32_e32 v78, v74, v34
	v_mul_f32_e32 v79, v74, v35
	v_mul_f32_e32 v76, v76, v124
	v_mul_f32_e32 v77, v77, v125
	v_mul_f32_e32 v78, v78, v126
	v_mul_f32_e32 v79, v79, v127
	global_store_dwordx4 v2, v[76:79], s[22:23] offset:2048
	v_mul_f32_e32 v80, v74, v36
	v_mul_f32_e32 v81, v74, v37
	v_mul_f32_e32 v82, v74, v38
	v_mul_f32_e32 v83, v74, v39
	v_mul_f32_e32 v80, v80, v128
	v_mul_f32_e32 v81, v81, v129
	v_mul_f32_e32 v82, v82, v130
	v_mul_f32_e32 v83, v83, v131
	global_store_dwordx4 v2, v[80:83], s[22:23] offset:3072
.Lfin_s0_skip:
	s_cmp_eq_u32 s29, 0
	s_cbranch_scc1 .Lfin_s1_skip
	v_mul_f32_e32 v76, v84, v40
	v_mul_f32_e32 v77, v84, v41
	v_mul_f32_e32 v78, v84, v42
	v_mul_f32_e32 v79, v84, v43
	v_mul_f32_e32 v76, v76, v100
	v_mul_f32_e32 v77, v77, v101
	v_mul_f32_e32 v78, v78, v102
	v_mul_f32_e32 v79, v79, v103
	global_store_dwordx4 v2, v[76:79], s[24:25]
	v_mul_f32_e32 v80, v84, v44
	v_mul_f32_e32 v81, v84, v45
	v_mul_f32_e32 v82, v84, v46
	v_mul_f32_e32 v83, v84, v47
	v_mul_f32_e32 v80, v80, v104
	v_mul_f32_e32 v81, v81, v105
	v_mul_f32_e32 v82, v82, v106
	v_mul_f32_e32 v83, v83, v107
	global_store_dwordx4 v2, v[80:83], s[24:25] offset:1024
	v_mul_f32_e32 v76, v84, v48
	v_mul_f32_e32 v77, v84, v49
	v_mul_f32_e32 v78, v84, v50
	v_mul_f32_e32 v79, v84, v51
	v_mul_f32_e32 v76, v76, v108
	v_mul_f32_e32 v77, v77, v109
	v_mul_f32_e32 v78, v78, v110
	v_mul_f32_e32 v79, v79, v111
	global_store_dwordx4 v2, v[76:79], s[24:25] offset:2048
	v_mul_f32_e32 v80, v84, v52
	v_mul_f32_e32 v81, v84, v53
	v_mul_f32_e32 v82, v84, v54
	v_mul_f32_e32 v83, v84, v55
	v_mul_f32_e32 v80, v80, v112
	v_mul_f32_e32 v81, v81, v113
	v_mul_f32_e32 v82, v82, v114
	v_mul_f32_e32 v83, v83, v115
	global_store_dwordx4 v2, v[80:83], s[24:25] offset:3072
	v_mul_f32_e32 v76, v84, v56
	v_mul_f32_e32 v77, v84, v57
	v_mul_f32_e32 v78, v84, v58
	v_mul_f32_e32 v79, v84, v59
	v_mul_f32_e32 v76, v76, v116
	v_mul_f32_e32 v77, v77, v117
	v_mul_f32_e32 v78, v78, v118
	v_mul_f32_e32 v79, v79, v119
	global_store_dwordx4 v2, v[76:79], s[26:27]
	v_mul_f32_e32 v80, v84, v60
	v_mul_f32_e32 v81, v84, v61
	v_mul_f32_e32 v82, v84, v62
	v_mul_f32_e32 v83, v84, v63
	v_mul_f32_e32 v80, v80, v120
	v_mul_f32_e32 v81, v81, v121
	v_mul_f32_e32 v82, v82, v122
	v_mul_f32_e32 v83, v83, v123
	global_store_dwordx4 v2, v[80:83], s[26:27] offset:1024
	v_mul_f32_e32 v76, v84, v64
	v_mul_f32_e32 v77, v84, v65
	v_mul_f32_e32 v78, v84, v66
	v_mul_f32_e32 v79, v84, v67
	v_mul_f32_e32 v76, v76, v124
	v_mul_f32_e32 v77, v77, v125
	v_mul_f32_e32 v78, v78, v126
	v_mul_f32_e32 v79, v79, v127
	global_store_dwordx4 v2, v[76:79], s[26:27] offset:2048
	v_mul_f32_e32 v80, v84, v68
	v_mul_f32_e32 v81, v84, v69
	v_mul_f32_e32 v82, v84, v70
	v_mul_f32_e32 v83, v84, v71
	v_mul_f32_e32 v80, v80, v128
	v_mul_f32_e32 v81, v81, v129
	v_mul_f32_e32 v82, v82, v130
	v_mul_f32_e32 v83, v83, v131
	global_store_dwordx4 v2, v[80:83], s[26:27] offset:3072
.Lfin_s1_skip:
	s_add_i32 s13, s13, s42
	v_readlane_b32 s0, v254, 16
	s_nop 1
	s_add_i32 s12, s12, s0
	s_cmpk_gt_i32 s13, 0x243
	s_cbranch_scc0 .Lfin_item
	s_mov_b64 s[0:1], 0
	s_branch .LBB0_61
